# gla_prep intra-chunk A tile: fragment LDS reads kept four deep ahead of the single-accumulator MFMA chain
# baseline (speedup 1.0000x reference)
.LBB0_548:
	s_or_b64 exec, exec, s[46:47]
	v_lshl_add_u64 v[0:1], s[66:67], 0, v[52:53]
	v_mov_b64_e32 v[8:9], s[54:55]
	v_mad_u64_u32 v[2:3], s[46:47], v0, s33, v[8:9]
	v_mad_i32_i24 v3, v1, s33, v3
	s_lshl_b32 s38, s38, 1
	v_lshl_add_u64 v[0:1], v[2:3], 0, s[38:39]
	v_lshl_add_u64 v[0:1], v[0:1], 0, v[160:161]
	flat_load_dwordx4 v[4:7], v[0:1]
	s_nop 0
	flat_load_dwordx4 v[0:3], v[0:1] offset:2048
	ds_read_b128 v[10:13], v130
	ds_read_b128 v[96:99], v130 offset:16
	ds_read_b128 v[138:141], v105
	ds_read_b128 v[142:145], v105 offset:16
	ds_read_b128 v[146:149], v106
	ds_read_b128 v[150:153], v106 offset:16
	s_mov_b32 s12, 0x3d800000
	s_waitcnt lgkmcnt(0)
	v_pk_add_f32 v[14:15], v[12:13], v[140:141]
	v_pk_add_f32 v[100:101], v[10:11], v[138:139]
	v_pk_add_f32 v[154:155], v[98:99], v[144:145]
	v_pk_add_f32 v[156:157], v[96:97], v[142:143]
	v_cndmask_b32_e64 v95, v99, v155, s[44:45]
	v_cndmask_b32_e64 v154, v98, v154, s[44:45]
	v_cndmask_b32_e64 v155, v97, v157, s[44:45]
	v_cndmask_b32_e64 v157, v13, v15, s[44:45]
	v_cndmask_b32_e64 v13, v10, v100, s[44:45]
	v_pk_add_f32 v[98:99], v[138:139], v[146:147]
	v_cndmask_b32_e64 v156, v96, v156, s[44:45]
	v_cndmask_b32_e64 v158, v12, v14, s[44:45]
	v_mul_f32_e32 v12, 0x3fb8aa3b, v13
	v_mul_f32_e32 v96, 0xbfb8aa3b, v13
	v_sub_f32_e32 v13, v98, v13
	v_cndmask_b32_e64 v159, v11, v101, s[44:45]
	v_mul_f32_e32 v13, 0x3fb8aa3b, v13
	v_exp_f32_e32 v98, v13
	v_mul_f32_e32 v13, 0x3fb8aa3b, v159
	v_exp_f32_e32 v12, v12
	v_exp_f32_e32 v13, v13
	v_exp_f32_e32 v96, v96
	v_pk_add_f32 v[100:101], v[140:141], v[148:149]
	v_pk_add_f32 v[14:15], v[142:143], v[150:151]
	v_sub_f32_e32 v101, v101, v157
	v_mul_f32_e32 v101, 0x3fb8aa3b, v101
	v_exp_f32_e32 v101, v101
	v_sub_f32_e32 v14, v14, v156
	v_mul_f32_e32 v14, 0x3fb8aa3b, v14
	v_exp_f32_e32 v14, v14
	v_pk_add_f32 v[10:11], v[144:145], v[152:153]
	s_waitcnt vmcnt(0)
	v_lshlrev_b32_e32 v138, 16, v4
	v_and_b32_e32 v139, 0xffff0000, v4
	v_pk_mul_f32 v[138:139], v[138:139], s[12:13] op_sel_hi:[1,0]
	v_mul_f32_e32 v4, 0xbfb8aa3b, v159
	v_pk_mul_f32 v[12:13], v[138:139], v[12:13]
	v_lshlrev_b32_e32 v138, 16, v0
	v_and_b32_e32 v139, 0xffff0000, v0
	v_sub_f32_e32 v0, v99, v159
	v_mul_f32_e32 v0, 0x3fb8aa3b, v0
	v_exp_f32_e32 v97, v4
	v_exp_f32_e32 v99, v0
	v_mul_f32_e32 v0, 0x3fb8aa3b, v158
	v_lshlrev_b32_e32 v4, 16, v5
	v_pk_mul_f32 v[96:97], v[96:97], v[138:139]
	v_pk_mul_f32 v[98:99], v[98:99], v[138:139]
	v_exp_f32_e32 v138, v0
	v_mul_f32_e32 v0, 0xbfb8aa3b, v158
	v_exp_f32_e32 v140, v0
	v_sub_f32_e32 v0, v100, v158
	v_mul_f32_e32 v0, 0x3fb8aa3b, v0
	v_exp_f32_e32 v100, v0
	v_mul_f32_e32 v0, 0x3fb8aa3b, v157
	v_exp_f32_e32 v139, v0
	v_mul_f32_e32 v0, 0xbfb8aa3b, v157
	v_exp_f32_e32 v141, v0
	v_and_b32_e32 v5, 0xffff0000, v5
	v_pk_mul_f32 v[4:5], v[4:5], s[12:13] op_sel_hi:[1,0]
	v_lshlrev_b32_e32 v142, 16, v6
	v_pk_mul_f32 v[4:5], v[4:5], v[138:139]
	v_lshlrev_b32_e32 v138, 16, v1
	v_and_b32_e32 v139, 0xffff0000, v1
	v_pk_mul_f32 v[0:1], v[140:141], v[138:139]
	v_pk_mul_f32 v[100:101], v[100:101], v[138:139]
	v_mul_f32_e32 v139, 0xbfb8aa3b, v156
	v_mul_f32_e32 v138, 0x3fb8aa3b, v156
	v_exp_f32_e32 v140, v139
	v_mul_f32_e32 v139, 0x3fb8aa3b, v155
	v_exp_f32_e32 v138, v138
	v_exp_f32_e32 v139, v139
	v_and_b32_e32 v143, 0xffff0000, v6
	v_pk_mul_f32 v[142:143], v[142:143], s[12:13] op_sel_hi:[1,0]
	v_mul_f32_e32 v6, 0xbfb8aa3b, v155
	v_pk_mul_f32 v[138:139], v[142:143], v[138:139]
	v_lshlrev_b32_e32 v142, 16, v2
	v_and_b32_e32 v143, 0xffff0000, v2
	v_sub_f32_e32 v2, v15, v155
	v_mul_f32_e32 v2, 0x3fb8aa3b, v2
	v_exp_f32_e32 v141, v6
	v_exp_f32_e32 v15, v2
	v_mul_f32_e32 v2, 0x3fb8aa3b, v154
	v_lshlrev_b32_e32 v144, 16, v7
	v_pk_mul_f32 v[140:141], v[140:141], v[142:143]
	v_pk_mul_f32 v[14:15], v[14:15], v[142:143]
	v_exp_f32_e32 v142, v2
	v_mul_f32_e32 v2, 0xbfb8aa3b, v154
	v_exp_f32_e32 v6, v2
	v_sub_f32_e32 v2, v10, v154
	v_mul_f32_e32 v10, 0x3fb8aa3b, v95
	v_exp_f32_e32 v143, v10
	v_and_b32_e32 v145, 0xffff0000, v7
	v_pk_mul_f32 v[144:145], v[144:145], s[12:13] op_sel_hi:[1,0]
	v_mul_f32_e32 v2, 0x3fb8aa3b, v2
	v_pk_mul_f32 v[142:143], v[144:145], v[142:143]
	v_lshlrev_b32_e32 v144, 16, v3
	v_and_b32_e32 v145, 0xffff0000, v3
	v_sub_f32_e32 v3, v11, v95
	v_mul_f32_e32 v7, 0xbfb8aa3b, v95
	v_mul_f32_e32 v3, 0x3fb8aa3b, v3
	v_exp_f32_e32 v2, v2
	v_exp_f32_e32 v7, v7
	v_exp_f32_e32 v3, v3
	v_pk_mul_f32 v[6:7], v[6:7], v[144:145]
	v_pk_mul_f32 v[10:11], v[2:3], v[144:145]
	v_cvt_pk_bf16_f32 v2, v12, v13
	v_cvt_pk_bf16_f32 v3, v4, v5
	v_cvt_pk_bf16_f32 v4, v138, v139
	v_cvt_pk_bf16_f32 v5, v142, v143
	ds_write2_b64 v107, v[2:3], v[4:5] offset1:2
	v_cvt_pk_bf16_f32 v2, v96, v97
	v_cvt_pk_bf16_f32 v3, v0, v1
	v_cvt_pk_bf16_f32 v0, v140, v141
	v_cvt_pk_bf16_f32 v1, v6, v7
	ds_write2_b64 v108, v[2:3], v[0:1] offset1:2
	v_cvt_pk_bf16_f32 v0, v98, v99
	v_cvt_pk_bf16_f32 v1, v100, v101
	v_cvt_pk_bf16_f32 v2, v14, v15
	v_cvt_pk_bf16_f32 v3, v10, v11
	ds_write_b128 v130, v[0:3]
	v_lshl_add_u64 v[0:1], s[66:67], 0, v[54:55]
	v_mad_u64_u32 v[2:3], s[46:47], v0, s33, v[8:9]
	v_mad_i32_i24 v3, v1, s33, v3
	v_lshl_add_u64 v[0:1], v[2:3], 0, s[38:39]
	v_lshl_add_u64 v[4:5], v[0:1], 0, v[160:161]
	flat_load_dwordx4 v[0:3], v[4:5]
	s_nop 0
	flat_load_dwordx4 v[4:7], v[4:5] offset:2048
	ds_read_b128 v[10:13], v131
	ds_read_b128 v[96:99], v131 offset:16
	ds_read_b128 v[138:141], v105
	ds_read_b128 v[142:145], v105 offset:16
	ds_read_b128 v[146:149], v106
	ds_read_b128 v[150:153], v106 offset:16
	s_waitcnt lgkmcnt(0)
	v_pk_add_f32 v[100:101], v[10:11], v[138:139]
	v_pk_add_f32 v[14:15], v[12:13], v[140:141]
	v_pk_add_f32 v[154:155], v[98:99], v[144:145]
	v_pk_add_f32 v[156:157], v[96:97], v[142:143]
	v_cndmask_b32_e64 v159, v11, v101, s[4:5]
	v_cndmask_b32_e64 v95, v99, v155, s[4:5]
	v_cndmask_b32_e64 v155, v97, v157, s[4:5]
	v_cndmask_b32_e64 v157, v13, v15, s[4:5]
	v_cndmask_b32_e64 v158, v12, v14, s[4:5]
	v_cndmask_b32_e64 v99, v10, v100, s[4:5]
	v_pk_add_f32 v[12:13], v[138:139], v[146:147]
	v_cndmask_b32_e64 v154, v98, v154, s[4:5]
	v_mul_f32_e32 v98, 0x3fb8aa3b, v99
	v_mul_f32_e32 v100, 0xbfb8aa3b, v99
	v_sub_f32_e32 v12, v12, v99
	v_mul_f32_e32 v99, 0x3fb8aa3b, v159
	v_exp_f32_e32 v98, v98
	v_mul_f32_e32 v12, 0x3fb8aa3b, v12
	v_exp_f32_e32 v99, v99
	v_exp_f32_e32 v100, v100
	v_exp_f32_e32 v12, v12
	v_pk_add_f32 v[10:11], v[140:141], v[148:149]
	v_cndmask_b32_e64 v156, v96, v156, s[4:5]
	v_pk_add_f32 v[96:97], v[142:143], v[150:151]
	v_pk_add_f32 v[14:15], v[144:145], v[152:153]
	s_waitcnt vmcnt(0)
	v_lshlrev_b32_e32 v138, 16, v0
	v_and_b32_e32 v139, 0xffff0000, v0
	v_mul_f32_e32 v0, 0xbfb8aa3b, v159
	v_exp_f32_e32 v101, v0
	v_sub_f32_e32 v0, v13, v159
	v_mul_f32_e32 v0, 0x3fb8aa3b, v0
	v_exp_f32_e32 v13, v0
	v_pk_mul_f32 v[138:139], v[138:139], s[12:13] op_sel_hi:[1,0]
	v_mul_f32_e32 v0, 0x3fb8aa3b, v158
	v_pk_mul_f32 v[98:99], v[138:139], v[98:99]
	v_lshlrev_b32_e32 v138, 16, v4
	v_and_b32_e32 v139, 0xffff0000, v4
	v_sub_f32_e32 v4, v10, v158
	v_mul_f32_e32 v10, 0x3fb8aa3b, v157
	v_pk_mul_f32 v[100:101], v[100:101], v[138:139]
	v_pk_mul_f32 v[12:13], v[12:13], v[138:139]
	v_exp_f32_e32 v138, v0
	v_exp_f32_e32 v139, v10
	v_lshlrev_b32_e32 v140, 16, v1
	v_and_b32_e32 v141, 0xffff0000, v1
	v_pk_mul_f32 v[140:141], v[140:141], s[12:13] op_sel_hi:[1,0]
	v_mul_f32_e32 v0, 0xbfb8aa3b, v158
	v_pk_mul_f32 v[138:139], v[140:141], v[138:139]
	v_lshlrev_b32_e32 v140, 16, v5
	v_and_b32_e32 v141, 0xffff0000, v5
	v_sub_f32_e32 v5, v11, v157
	v_mul_f32_e32 v4, 0x3fb8aa3b, v4
	v_mul_f32_e32 v1, 0xbfb8aa3b, v157
	v_mul_f32_e32 v5, 0x3fb8aa3b, v5
	v_exp_f32_e32 v0, v0
	v_exp_f32_e32 v4, v4
	v_exp_f32_e32 v1, v1
	v_exp_f32_e32 v5, v5
	v_mul_f32_e32 v11, 0xbfb8aa3b, v156
	v_lshlrev_b32_e32 v142, 16, v2
	v_pk_mul_f32 v[0:1], v[0:1], v[140:141]
	v_pk_mul_f32 v[4:5], v[4:5], v[140:141]
	v_exp_f32_e32 v140, v11
	v_sub_f32_e32 v11, v96, v156
	v_mul_f32_e32 v11, 0x3fb8aa3b, v11
	v_and_b32_e32 v143, 0xffff0000, v2
	v_mul_f32_e32 v2, 0xbfb8aa3b, v155
	v_mul_f32_e32 v10, 0x3fb8aa3b, v156
	v_exp_f32_e32 v96, v11
	v_mul_f32_e32 v11, 0x3fb8aa3b, v155
	v_exp_f32_e32 v141, v2
	v_sub_f32_e32 v2, v97, v155
	v_exp_f32_e32 v10, v10
	v_exp_f32_e32 v11, v11
	v_mul_f32_e32 v2, 0x3fb8aa3b, v2
	v_exp_f32_e32 v97, v2
	v_pk_mul_f32 v[142:143], v[142:143], s[12:13] op_sel_hi:[1,0]
	v_mul_f32_e32 v2, 0x3fb8aa3b, v154
	v_pk_mul_f32 v[10:11], v[142:143], v[10:11]
	v_lshlrev_b32_e32 v142, 16, v6
	v_and_b32_e32 v143, 0xffff0000, v6
	v_sub_f32_e32 v6, v14, v154
	v_mul_f32_e32 v14, 0x3fb8aa3b, v95
	v_pk_mul_f32 v[140:141], v[140:141], v[142:143]
	v_pk_mul_f32 v[96:97], v[96:97], v[142:143]
	v_exp_f32_e32 v142, v2
	v_exp_f32_e32 v143, v14
	v_lshlrev_b32_e32 v144, 16, v3
	v_and_b32_e32 v145, 0xffff0000, v3
	v_pk_mul_f32 v[144:145], v[144:145], s[12:13] op_sel_hi:[1,0]
	v_mul_f32_e32 v2, 0xbfb8aa3b, v154
	v_pk_mul_f32 v[142:143], v[144:145], v[142:143]
	v_mul_f32_e32 v3, 0xbfb8aa3b, v95
	v_lshlrev_b32_e32 v144, 16, v7
	v_and_b32_e32 v145, 0xffff0000, v7
	v_sub_f32_e32 v7, v15, v95
	v_exp_f32_e32 v2, v2
	v_mul_f32_e32 v6, 0x3fb8aa3b, v6
	v_exp_f32_e32 v3, v3
	v_mul_f32_e32 v7, 0x3fb8aa3b, v7
	v_exp_f32_e32 v6, v6
	v_exp_f32_e32 v7, v7
	v_pk_mul_f32 v[2:3], v[2:3], v[144:145]
	v_cvt_pk_bf16_f32 v14, v98, v99
	v_cvt_pk_bf16_f32 v15, v138, v139
	v_cvt_pk_bf16_f32 v10, v10, v11
	v_cvt_pk_bf16_f32 v11, v142, v143
	v_pk_mul_f32 v[6:7], v[6:7], v[144:145]
	ds_write2_b64 v109, v[14:15], v[10:11] offset1:2
	v_cvt_pk_bf16_f32 v10, v100, v101
	v_cvt_pk_bf16_f32 v11, v0, v1
	v_cvt_pk_bf16_f32 v0, v140, v141
	v_cvt_pk_bf16_f32 v1, v2, v3
	ds_write2_b64 v110, v[10:11], v[0:1] offset1:2
	v_cvt_pk_bf16_f32 v0, v12, v13
	v_cvt_pk_bf16_f32 v1, v4, v5
	v_cvt_pk_bf16_f32 v2, v96, v97
	v_cvt_pk_bf16_f32 v3, v6, v7
	ds_write_b128 v131, v[0:3]
	v_lshl_add_u64 v[0:1], s[66:67], 0, v[56:57]
	v_mad_u64_u32 v[2:3], s[46:47], v0, s33, v[8:9]
	v_mad_i32_i24 v3, v1, s33, v3
	v_lshl_add_u64 v[0:1], v[2:3], 0, s[38:39]
	v_lshl_add_u64 v[4:5], v[0:1], 0, v[160:161]
	flat_load_dwordx4 v[0:3], v[4:5]
	s_nop 0
	flat_load_dwordx4 v[4:7], v[4:5] offset:2048
	ds_read_b128 v[10:13], v132
	ds_read_b128 v[96:99], v132 offset:16
	ds_read_b128 v[138:141], v105
	ds_read_b128 v[142:145], v105 offset:16
	ds_read_b128 v[146:149], v106
	ds_read_b128 v[150:153], v106 offset:16
	s_waitcnt lgkmcnt(0)
	v_pk_add_f32 v[100:101], v[10:11], v[138:139]
	v_pk_add_f32 v[14:15], v[12:13], v[140:141]
	v_pk_add_f32 v[154:155], v[98:99], v[144:145]
	v_pk_add_f32 v[156:157], v[96:97], v[142:143]
	v_cndmask_b32_e64 v159, v11, v101, s[6:7]
	v_cndmask_b32_e64 v95, v99, v155, s[6:7]
	v_cndmask_b32_e64 v155, v97, v157, s[6:7]
	v_cndmask_b32_e64 v157, v13, v15, s[6:7]
	v_cndmask_b32_e64 v158, v12, v14, s[6:7]
	v_cndmask_b32_e64 v99, v10, v100, s[6:7]
	v_pk_add_f32 v[12:13], v[138:139], v[146:147]
	v_cndmask_b32_e64 v154, v98, v154, s[6:7]
	v_mul_f32_e32 v98, 0x3fb8aa3b, v99
	v_mul_f32_e32 v100, 0xbfb8aa3b, v99
	v_sub_f32_e32 v12, v12, v99
	v_mul_f32_e32 v99, 0x3fb8aa3b, v159
	v_exp_f32_e32 v98, v98
	v_mul_f32_e32 v12, 0x3fb8aa3b, v12
	v_exp_f32_e32 v99, v99
	v_exp_f32_e32 v100, v100
	v_exp_f32_e32 v12, v12
	v_pk_add_f32 v[10:11], v[140:141], v[148:149]
	v_cndmask_b32_e64 v156, v96, v156, s[6:7]
	v_pk_add_f32 v[96:97], v[142:143], v[150:151]
	v_pk_add_f32 v[14:15], v[144:145], v[152:153]
	s_waitcnt vmcnt(0)
	v_lshlrev_b32_e32 v138, 16, v0
	v_and_b32_e32 v139, 0xffff0000, v0
	v_mul_f32_e32 v0, 0xbfb8aa3b, v159
	v_exp_f32_e32 v101, v0
	v_sub_f32_e32 v0, v13, v159
	v_mul_f32_e32 v0, 0x3fb8aa3b, v0
	v_exp_f32_e32 v13, v0
	v_pk_mul_f32 v[138:139], v[138:139], s[12:13] op_sel_hi:[1,0]
	v_mul_f32_e32 v0, 0x3fb8aa3b, v158
	v_pk_mul_f32 v[98:99], v[138:139], v[98:99]
	v_lshlrev_b32_e32 v138, 16, v4
	v_and_b32_e32 v139, 0xffff0000, v4
	v_sub_f32_e32 v4, v10, v158
	v_mul_f32_e32 v10, 0x3fb8aa3b, v157
	v_pk_mul_f32 v[100:101], v[100:101], v[138:139]
	v_pk_mul_f32 v[12:13], v[12:13], v[138:139]
	v_exp_f32_e32 v138, v0
	v_exp_f32_e32 v139, v10
	v_lshlrev_b32_e32 v140, 16, v1
	v_and_b32_e32 v141, 0xffff0000, v1
	v_pk_mul_f32 v[140:141], v[140:141], s[12:13] op_sel_hi:[1,0]
	v_mul_f32_e32 v0, 0xbfb8aa3b, v158
	v_pk_mul_f32 v[138:139], v[140:141], v[138:139]
	v_lshlrev_b32_e32 v140, 16, v5
	v_and_b32_e32 v141, 0xffff0000, v5
	v_sub_f32_e32 v5, v11, v157
	v_mul_f32_e32 v4, 0x3fb8aa3b, v4
	v_mul_f32_e32 v1, 0xbfb8aa3b, v157
	v_mul_f32_e32 v5, 0x3fb8aa3b, v5
	v_exp_f32_e32 v0, v0
	v_exp_f32_e32 v4, v4
	v_exp_f32_e32 v1, v1
	v_exp_f32_e32 v5, v5
	v_mul_f32_e32 v11, 0xbfb8aa3b, v156
	v_lshlrev_b32_e32 v142, 16, v2
	v_pk_mul_f32 v[0:1], v[0:1], v[140:141]
	v_pk_mul_f32 v[4:5], v[4:5], v[140:141]
	v_exp_f32_e32 v140, v11
	v_sub_f32_e32 v11, v96, v156
	v_mul_f32_e32 v11, 0x3fb8aa3b, v11
	v_and_b32_e32 v143, 0xffff0000, v2
	v_mul_f32_e32 v2, 0xbfb8aa3b, v155
	v_mul_f32_e32 v10, 0x3fb8aa3b, v156
	v_exp_f32_e32 v96, v11
	v_mul_f32_e32 v11, 0x3fb8aa3b, v155
	v_exp_f32_e32 v141, v2
	v_sub_f32_e32 v2, v97, v155
	v_exp_f32_e32 v10, v10
	v_exp_f32_e32 v11, v11
	v_mul_f32_e32 v2, 0x3fb8aa3b, v2
	v_exp_f32_e32 v97, v2
	v_pk_mul_f32 v[142:143], v[142:143], s[12:13] op_sel_hi:[1,0]
	v_mul_f32_e32 v2, 0x3fb8aa3b, v154
	v_pk_mul_f32 v[10:11], v[142:143], v[10:11]
	v_lshlrev_b32_e32 v142, 16, v6
	v_and_b32_e32 v143, 0xffff0000, v6
	v_sub_f32_e32 v6, v14, v154
	v_mul_f32_e32 v14, 0x3fb8aa3b, v95
	v_pk_mul_f32 v[140:141], v[140:141], v[142:143]
	v_pk_mul_f32 v[96:97], v[96:97], v[142:143]
	v_exp_f32_e32 v142, v2
	v_exp_f32_e32 v143, v14
	v_lshlrev_b32_e32 v144, 16, v3
	v_and_b32_e32 v145, 0xffff0000, v3
	v_pk_mul_f32 v[144:145], v[144:145], s[12:13] op_sel_hi:[1,0]
	v_mul_f32_e32 v2, 0xbfb8aa3b, v154
	v_pk_mul_f32 v[142:143], v[144:145], v[142:143]
	v_mul_f32_e32 v3, 0xbfb8aa3b, v95
	v_lshlrev_b32_e32 v144, 16, v7
	v_and_b32_e32 v145, 0xffff0000, v7
	v_sub_f32_e32 v7, v15, v95
	v_exp_f32_e32 v2, v2
	v_mul_f32_e32 v6, 0x3fb8aa3b, v6
	v_exp_f32_e32 v3, v3
	v_mul_f32_e32 v7, 0x3fb8aa3b, v7
	v_exp_f32_e32 v6, v6
	v_exp_f32_e32 v7, v7
	v_pk_mul_f32 v[2:3], v[2:3], v[144:145]
	v_cvt_pk_bf16_f32 v14, v98, v99
	v_cvt_pk_bf16_f32 v15, v138, v139
	v_cvt_pk_bf16_f32 v10, v10, v11
	v_cvt_pk_bf16_f32 v11, v142, v143
	v_pk_mul_f32 v[6:7], v[6:7], v[144:145]
	ds_write2_b64 v111, v[14:15], v[10:11] offset1:2
	v_cvt_pk_bf16_f32 v10, v100, v101
	v_cvt_pk_bf16_f32 v11, v0, v1
	v_cvt_pk_bf16_f32 v0, v140, v141
	v_cvt_pk_bf16_f32 v1, v2, v3
	ds_write2_b64 v112, v[10:11], v[0:1] offset1:2
	v_cvt_pk_bf16_f32 v0, v12, v13
	v_cvt_pk_bf16_f32 v1, v4, v5
	v_cvt_pk_bf16_f32 v2, v96, v97
	v_cvt_pk_bf16_f32 v3, v6, v7
	ds_write_b128 v132, v[0:3]
	v_lshl_add_u64 v[0:1], s[66:67], 0, v[58:59]
	v_mad_u64_u32 v[2:3], s[46:47], v0, s33, v[8:9]
	v_mad_i32_i24 v3, v1, s33, v3
	v_lshl_add_u64 v[0:1], v[2:3], 0, s[38:39]
	v_lshl_add_u64 v[4:5], v[0:1], 0, v[160:161]
	flat_load_dwordx4 v[0:3], v[4:5]
	s_nop 0
	flat_load_dwordx4 v[4:7], v[4:5] offset:2048
	ds_read_b128 v[8:11], v133
	ds_read_b128 v[12:15], v133 offset:16
	ds_read_b128 v[96:99], v105
	ds_read_b128 v[138:141], v105 offset:16
	ds_read_b128 v[142:145], v106
	ds_read_b128 v[146:149], v106 offset:16
	s_lshl_b64 s[46:47], s[64:65], 15
	s_waitcnt lgkmcnt(0)
	v_pk_add_f32 v[100:101], v[10:11], v[98:99]
	v_pk_add_f32 v[150:151], v[8:9], v[96:97]
	v_pk_add_f32 v[152:153], v[14:15], v[140:141]
	v_pk_add_f32 v[154:155], v[12:13], v[138:139]
	v_cndmask_b32_e64 v95, v15, v153, s[8:9]
	v_cndmask_b32_e64 v153, v13, v155, s[8:9]
	v_cndmask_b32_e64 v155, v11, v101, s[8:9]
	v_cndmask_b32_e64 v156, v10, v100, s[8:9]
	v_cndmask_b32_e64 v151, v9, v151, s[8:9]
	v_cndmask_b32_e64 v100, v8, v150, s[8:9]
	v_pk_add_f32 v[10:11], v[96:97], v[142:143]
	v_mul_f32_e32 v96, 0x3fb8aa3b, v100
	v_mul_f32_e32 v97, 0xbfb8aa3b, v100
	v_sub_f32_e32 v10, v10, v100
	v_pk_add_f32 v[8:9], v[98:99], v[144:145]
	v_exp_f32_e32 v98, v97
	v_mul_f32_e32 v97, 0x3fb8aa3b, v151
	v_exp_f32_e32 v96, v96
	v_mul_f32_e32 v10, 0x3fb8aa3b, v10
	v_exp_f32_e32 v97, v97
	v_exp_f32_e32 v10, v10
	v_cndmask_b32_e64 v152, v14, v152, s[8:9]
	v_pk_add_f32 v[14:15], v[138:139], v[146:147]
	v_cndmask_b32_e64 v154, v12, v154, s[8:9]
	v_pk_add_f32 v[12:13], v[140:141], v[148:149]
	s_add_u32 s66, s74, s46
	s_addc_u32 s67, s75, s47
	s_add_u32 s46, s76, s46
	s_addc_u32 s47, s77, s47
	s_andn2_b64 vcc, exec, s[60:61]
	s_waitcnt vmcnt(0)
	v_lshlrev_b32_e32 v100, 16, v0
	v_and_b32_e32 v101, 0xffff0000, v0
	v_mul_f32_e32 v0, 0xbfb8aa3b, v151
	v_exp_f32_e32 v99, v0
	v_sub_f32_e32 v0, v11, v151
	v_mul_f32_e32 v0, 0x3fb8aa3b, v0
	v_exp_f32_e32 v11, v0
	v_pk_mul_f32 v[100:101], v[100:101], s[12:13] op_sel_hi:[1,0]
	v_mul_f32_e32 v0, 0x3fb8aa3b, v156
	v_pk_mul_f32 v[96:97], v[100:101], v[96:97]
	v_lshlrev_b32_e32 v100, 16, v4
	v_and_b32_e32 v101, 0xffff0000, v4
	v_sub_f32_e32 v4, v8, v156
	v_mul_f32_e32 v8, 0x3fb8aa3b, v155
	v_pk_mul_f32 v[98:99], v[98:99], v[100:101]
	v_pk_mul_f32 v[10:11], v[10:11], v[100:101]
	v_exp_f32_e32 v100, v0
	v_exp_f32_e32 v101, v8
	v_lshlrev_b32_e32 v138, 16, v1
	v_and_b32_e32 v139, 0xffff0000, v1
	v_pk_mul_f32 v[138:139], v[138:139], s[12:13] op_sel_hi:[1,0]
	v_mul_f32_e32 v0, 0xbfb8aa3b, v156
	v_pk_mul_f32 v[100:101], v[138:139], v[100:101]
	v_lshlrev_b32_e32 v138, 16, v5
	v_and_b32_e32 v139, 0xffff0000, v5
	v_sub_f32_e32 v5, v9, v155
	v_mul_f32_e32 v4, 0x3fb8aa3b, v4
	v_mul_f32_e32 v1, 0xbfb8aa3b, v155
	v_mul_f32_e32 v5, 0x3fb8aa3b, v5
	v_exp_f32_e32 v0, v0
	v_exp_f32_e32 v4, v4
	v_exp_f32_e32 v1, v1
	v_exp_f32_e32 v5, v5
	v_mul_f32_e32 v9, 0xbfb8aa3b, v154
	v_lshlrev_b32_e32 v140, 16, v2
	v_pk_mul_f32 v[0:1], v[0:1], v[138:139]
	v_pk_mul_f32 v[4:5], v[4:5], v[138:139]
	v_exp_f32_e32 v138, v9
	v_sub_f32_e32 v9, v14, v154
	v_mul_f32_e32 v9, 0x3fb8aa3b, v9
	v_and_b32_e32 v141, 0xffff0000, v2
	v_mul_f32_e32 v2, 0xbfb8aa3b, v153
	v_mul_f32_e32 v8, 0x3fb8aa3b, v154
	v_exp_f32_e32 v14, v9
	v_mul_f32_e32 v9, 0x3fb8aa3b, v153
	v_exp_f32_e32 v139, v2
	v_sub_f32_e32 v2, v15, v153
	v_exp_f32_e32 v8, v8
	v_exp_f32_e32 v9, v9
	v_mul_f32_e32 v2, 0x3fb8aa3b, v2
	v_exp_f32_e32 v15, v2
	v_pk_mul_f32 v[140:141], v[140:141], s[12:13] op_sel_hi:[1,0]
	v_mul_f32_e32 v2, 0x3fb8aa3b, v152
	v_pk_mul_f32 v[8:9], v[140:141], v[8:9]
	v_lshlrev_b32_e32 v140, 16, v6
	v_and_b32_e32 v141, 0xffff0000, v6
	v_sub_f32_e32 v6, v12, v152
	v_mul_f32_e32 v12, 0x3fb8aa3b, v95
	v_pk_mul_f32 v[138:139], v[138:139], v[140:141]
	v_pk_mul_f32 v[14:15], v[14:15], v[140:141]
	v_exp_f32_e32 v140, v2
	v_exp_f32_e32 v141, v12
	v_lshlrev_b32_e32 v142, 16, v3
	v_and_b32_e32 v143, 0xffff0000, v3
	v_pk_mul_f32 v[142:143], v[142:143], s[12:13] op_sel_hi:[1,0]
	v_mul_f32_e32 v2, 0xbfb8aa3b, v152
	v_pk_mul_f32 v[140:141], v[142:143], v[140:141]
	v_mul_f32_e32 v3, 0xbfb8aa3b, v95
	v_lshlrev_b32_e32 v142, 16, v7
	v_and_b32_e32 v143, 0xffff0000, v7
	v_sub_f32_e32 v7, v13, v95
	v_exp_f32_e32 v2, v2
	v_mul_f32_e32 v6, 0x3fb8aa3b, v6
	v_exp_f32_e32 v3, v3
	v_mul_f32_e32 v7, 0x3fb8aa3b, v7
	v_exp_f32_e32 v6, v6
	v_exp_f32_e32 v7, v7
	v_pk_mul_f32 v[2:3], v[2:3], v[142:143]
	v_cvt_pk_bf16_f32 v12, v96, v97
	v_cvt_pk_bf16_f32 v13, v100, v101
	v_cvt_pk_bf16_f32 v8, v8, v9
	v_cvt_pk_bf16_f32 v9, v140, v141
	v_pk_mul_f32 v[6:7], v[6:7], v[142:143]
	ds_write2_b64 v113, v[12:13], v[8:9] offset1:2
	v_cvt_pk_bf16_f32 v8, v98, v99
	v_cvt_pk_bf16_f32 v9, v0, v1
	v_cvt_pk_bf16_f32 v0, v138, v139
	v_cvt_pk_bf16_f32 v1, v2, v3
	ds_write2_b64 v114, v[8:9], v[0:1] offset1:2
	v_cvt_pk_bf16_f32 v0, v10, v11
	v_cvt_pk_bf16_f32 v1, v4, v5
	v_cvt_pk_bf16_f32 v2, v14, v15
	v_cvt_pk_bf16_f32 v3, v6, v7
	ds_write_b128 v133, v[0:3]
	s_waitcnt lgkmcnt(0)
	s_barrier
	ds_read_b128 v[0:3], v115
	v_lshlrev_b64 v[4:5], 1, v[36:37]
	v_lshl_add_u64 v[6:7], s[66:67], 0, v[4:5]
	v_lshl_add_u64 v[4:5], s[46:47], 0, v[4:5]
	s_waitcnt lgkmcnt(0)
	flat_store_dwordx4 v[6:7], v[0:3]
	ds_read_b128 v[0:3], v116
	v_lshlrev_b64 v[6:7], 1, v[38:39]
	v_lshl_add_u64 v[8:9], s[66:67], 0, v[6:7]
	s_waitcnt lgkmcnt(0)
	flat_store_dwordx4 v[8:9], v[0:3]
	ds_read_b128 v[0:3], v117
	v_lshlrev_b64 v[8:9], 1, v[40:41]
	v_lshl_add_u64 v[10:11], s[66:67], 0, v[8:9]
	s_waitcnt lgkmcnt(0)
	flat_store_dwordx4 v[10:11], v[0:3]
	ds_read_b128 v[0:3], v118
	v_lshlrev_b64 v[10:11], 1, v[42:43]
	v_lshl_add_u64 v[12:13], s[66:67], 0, v[10:11]
	s_waitcnt lgkmcnt(0)
	flat_store_dwordx4 v[12:13], v[0:3]
	ds_read_u16 v0, v134
	ds_read_u16 v1, v134 offset:1024
	s_waitcnt lgkmcnt(0)
	v_lshl_or_b32 v0, v1, 16, v0
	ds_read_u16 v1, v134 offset:2048
	ds_read_u16 v2, v134 offset:3072
	s_waitcnt lgkmcnt(0)
	v_lshl_or_b32 v1, v2, 16, v1
	ds_read_u16 v2, v134 offset:4096
	ds_read_u16 v3, v134 offset:5120
	s_waitcnt lgkmcnt(0)
	v_lshl_or_b32 v2, v3, 16, v2
	ds_read_u16 v3, v134 offset:6144
	ds_read_u16 v12, v134 offset:7168
	s_waitcnt lgkmcnt(0)
	v_lshl_or_b32 v3, v12, 16, v3
	flat_store_dwordx4 v[4:5], v[0:3]
	ds_read_u16 v0, v135
	ds_read_u16 v1, v135 offset:1024
	s_waitcnt lgkmcnt(0)
	v_lshl_or_b32 v0, v1, 16, v0
	ds_read_u16 v1, v135 offset:2048
	ds_read_u16 v2, v135 offset:3072
	s_waitcnt lgkmcnt(0)
	v_lshl_or_b32 v1, v2, 16, v1
	ds_read_u16 v2, v135 offset:4096
	ds_read_u16 v3, v135 offset:5120
	s_waitcnt lgkmcnt(0)
	v_lshl_or_b32 v2, v3, 16, v2
	ds_read_u16 v3, v135 offset:6144
	ds_read_u16 v4, v135 offset:7168
	s_waitcnt lgkmcnt(0)
	v_lshl_or_b32 v3, v4, 16, v3
	v_lshl_add_u64 v[4:5], s[46:47], 0, v[6:7]
	flat_store_dwordx4 v[4:5], v[0:3]
	ds_read_u16 v0, v136
	ds_read_u16 v1, v136 offset:1024
	s_waitcnt lgkmcnt(0)
	v_lshl_or_b32 v0, v1, 16, v0
	ds_read_u16 v1, v136 offset:2048
	ds_read_u16 v2, v136 offset:3072
	s_waitcnt lgkmcnt(0)
	v_lshl_or_b32 v1, v2, 16, v1
	ds_read_u16 v2, v136 offset:4096
	ds_read_u16 v3, v136 offset:5120
	s_waitcnt lgkmcnt(0)
	v_lshl_or_b32 v2, v3, 16, v2
	ds_read_u16 v3, v136 offset:6144
	ds_read_u16 v4, v136 offset:7168
	s_waitcnt lgkmcnt(0)
	v_lshl_or_b32 v3, v4, 16, v3
	v_lshl_add_u64 v[4:5], s[46:47], 0, v[8:9]
	flat_store_dwordx4 v[4:5], v[0:3]
	ds_read_u16 v0, v137
	ds_read_u16 v1, v137 offset:1024
	s_waitcnt lgkmcnt(0)
	v_lshl_or_b32 v0, v1, 16, v0
	ds_read_u16 v1, v137 offset:2048
	ds_read_u16 v2, v137 offset:3072
	s_waitcnt lgkmcnt(0)
	v_lshl_or_b32 v1, v2, 16, v1
	ds_read_u16 v2, v137 offset:4096
	ds_read_u16 v3, v137 offset:5120
	s_waitcnt lgkmcnt(0)
	v_lshl_or_b32 v2, v3, 16, v2
	ds_read_u16 v3, v137 offset:6144
	ds_read_u16 v4, v137 offset:7168
	s_waitcnt lgkmcnt(0)
	v_lshl_or_b32 v3, v4, 16, v3
	v_lshl_add_u64 v[4:5], s[46:47], 0, v[10:11]
	flat_store_dwordx4 v[4:5], v[0:3]
	s_cbranch_vccnz .LBB0_541
	v_readlane_b32 s12, v255, 17
	v_readlane_b32 s13, v255, 18
	v_mov_b32_e32 v0, 0
	s_andn2_b64 vcc, exec, s[12:13]
	v_mov_b32_e32 v1, 0
	v_mov_b32_e32 v2, 0
	v_mov_b32_e32 v3, 0
	v_mov_b32_e32 v4, 0
	v_mov_b32_e32 v5, 0
	v_mov_b32_e32 v6, 0
	v_mov_b32_e32 v7, 0
	v_mov_b32_e32 v8, 0
	v_mov_b32_e32 v9, 0
	v_mov_b32_e32 v10, 0
	v_mov_b32_e32 v11, 0
	v_mov_b32_e32 v12, 0
	v_mov_b32_e32 v13, 0
	v_mov_b32_e32 v14, 0
	v_mov_b32_e32 v15, 0
	s_cbranch_vccnz .LBB0_540
	ds_read_b128 v[96:99], v119
	ds_read_b128 v[138:141], v120
	ds_read_b128 v[200:203], v119 offset:32
	ds_read_b128 v[212:215], v120 offset:32
	ds_read_b128 v[204:207], v119 offset:64
	ds_read_b128 v[216:219], v120 offset:64
	ds_read_b128 v[208:211], v119 offset:96
	ds_read_b128 v[220:223], v120 offset:96
	s_waitcnt lgkmcnt(6)
	v_mfma_f32_32x32x16_bf16 v[0:15], v[96:99], v[138:141], 0
	ds_read_b128 v[96:99], v119 offset:128
	ds_read_b128 v[138:141], v120 offset:128
	s_waitcnt lgkmcnt(6)
	v_mfma_f32_32x32x16_bf16 v[0:15], v[200:203], v[212:215], v[0:15]
	ds_read_b128 v[200:203], v119 offset:160
	ds_read_b128 v[212:215], v120 offset:160
	s_waitcnt lgkmcnt(6)
	v_mfma_f32_32x32x16_bf16 v[0:15], v[204:207], v[216:219], v[0:15]
	ds_read_b128 v[204:207], v119 offset:192
	ds_read_b128 v[216:219], v120 offset:192
	s_waitcnt lgkmcnt(6)
	v_mfma_f32_32x32x16_bf16 v[0:15], v[208:211], v[220:223], v[0:15]
	ds_read_b128 v[208:211], v119 offset:224
	ds_read_b128 v[220:223], v120 offset:224
	s_waitcnt lgkmcnt(6)
	v_mfma_f32_32x32x16_bf16 v[0:15], v[96:99], v[138:141], v[0:15]
	ds_read_b128 v[96:99], v119 offset:256
	ds_read_b128 v[138:141], v120 offset:256
	s_waitcnt lgkmcnt(6)
	v_mfma_f32_32x32x16_bf16 v[0:15], v[200:203], v[212:215], v[0:15]
	ds_read_b128 v[200:203], v119 offset:288
	ds_read_b128 v[212:215], v120 offset:288
	s_waitcnt lgkmcnt(6)
	v_mfma_f32_32x32x16_bf16 v[0:15], v[204:207], v[216:219], v[0:15]
	ds_read_b128 v[204:207], v119 offset:320
	ds_read_b128 v[216:219], v120 offset:320
	s_waitcnt lgkmcnt(6)
	v_mfma_f32_32x32x16_bf16 v[0:15], v[208:211], v[220:223], v[0:15]
	ds_read_b128 v[208:211], v119 offset:352
	ds_read_b128 v[220:223], v120 offset:352
	s_waitcnt lgkmcnt(6)
	v_mfma_f32_32x32x16_bf16 v[0:15], v[96:99], v[138:141], v[0:15]
	ds_read_b128 v[96:99], v119 offset:384
	ds_read_b128 v[138:141], v120 offset:384
	s_waitcnt lgkmcnt(6)
	v_mfma_f32_32x32x16_bf16 v[0:15], v[200:203], v[212:215], v[0:15]
	ds_read_b128 v[200:203], v119 offset:416
	ds_read_b128 v[212:215], v120 offset:416
	s_waitcnt lgkmcnt(6)
	v_mfma_f32_32x32x16_bf16 v[0:15], v[204:207], v[216:219], v[0:15]
	ds_read_b128 v[204:207], v119 offset:448
	ds_read_b128 v[216:219], v120 offset:448
	s_waitcnt lgkmcnt(6)
	v_mfma_f32_32x32x16_bf16 v[0:15], v[208:211], v[220:223], v[0:15]
	ds_read_b128 v[208:211], v119 offset:480
	ds_read_b128 v[220:223], v120 offset:480
	s_waitcnt lgkmcnt(6)
	v_mfma_f32_32x32x16_bf16 v[0:15], v[96:99], v[138:141], v[0:15]
	s_waitcnt lgkmcnt(4)
	v_mfma_f32_32x32x16_bf16 v[0:15], v[200:203], v[212:215], v[0:15]
	s_waitcnt lgkmcnt(2)
	v_mfma_f32_32x32x16_bf16 v[0:15], v[204:207], v[216:219], v[0:15]
	s_waitcnt lgkmcnt(0)
	v_mfma_f32_32x32x16_bf16 v[0:15], v[208:211], v[220:223], v[0:15]
	s_branch .LBB0_540
